# v26 ordering plus chunk-edge overlap: barrier and next-chunk operand loads ahead of the y reduction
# speedup vs baseline: 1.0029x; 1.0013x over previous
.LBB0_682:
	s_bitcmp1_b32 s30, 0
	s_cselect_b32 s6, 0xe000, 0
	s_add_i32 s6, s6, 0
	v_add_u32_e32 v90, s6, v58
	v_sub_u32_e32 v88, v90, v61
	v_add_u32_e32 v89, s6, v86
	ds_read_b128 v[4:7], v90 offset:0x4000
	ds_read_b128 v[8:11], v90 offset:0x0
	ds_read2st64_b32 v[108:109], v89 offset0:192 offset1:193
	ds_read2st64_b64 v[100:103], v88 offset0:64 offset1:65
	ds_read_b128 v[112:115], v90 offset:0x4200
	ds_read_b128 v[96:99], v90 offset:0x200
	v_mov_b32_e32 v93, v91
	ds_read_b128 v[120:123], v90 offset:0x4400
	ds_read_b128 v[124:127], v90 offset:0x400
	s_waitcnt lgkmcnt(5)
.Lrw_steps:
	v_pk_mul_f32 v[0:1], v[52:53], v[4:5] op_sel_hi:[0,1]
	v_pk_fma_f32 v[0:1], v[52:53], v[6:7], v[0:1] op_sel:[1,0,0]
	v_pk_mul_f32 v[10:11], v[108:109], v[10:11] op_sel_hi:[0,1]
	v_pk_fma_f32 v[54:55], v[52:53], v[8:9], v[10:11]
	v_add_f32_dpp v0, v0, v0 quad_perm:[1,0,3,2] row_mask:0xf bank_mask:0xf bound_ctrl:1
	v_add_f32_dpp v1, v1, v1 quad_perm:[1,0,3,2] row_mask:0xf bank_mask:0xf bound_ctrl:1
	s_nop 0
	ds_read_b128 v[4:7], v90 offset:0x4600
	v_add_f32_dpp v0, v0, v0 quad_perm:[2,3,0,1] row_mask:0xf bank_mask:0xf bound_ctrl:1
	s_nop 0
	ds_read_b128 v[8:11], v90 offset:0x600
	v_add_f32_dpp v0, v0, v0 row_half_mirror row_mask:0xf bank_mask:0xf bound_ctrl:1
	s_nop 0
	ds_read2st64_b32 v[110:111], v89 offset0:194 offset1:195
	ds_read2st64_b64 v[104:107], v88 offset0:66 offset1:67
	v_add_f32_dpp v2, v0, v0 row_mirror row_mask:0xf bank_mask:0xf bound_ctrl:1
	v_add_f32_dpp v0, v0, v0 row_mirror row_mask:0xf bank_mask:0xf bound_ctrl:1
	s_nop 0
	s_waitcnt lgkmcnt(6)
	v_permlane16_swap_b32_e32 v0, v2
	v_add_f32_e32 v0, v0, v2
	v_pk_fma_f32 v[52:53], v[100:101], v[0:1], v[54:55] op_sel_hi:[1,0,1]
	v_pk_mul_f32 v[118:119], v[52:53], v[112:113] op_sel_hi:[0,1]
	v_pk_fma_f32 v[118:119], v[52:53], v[114:115], v[118:119] op_sel:[1,0,0]
	v_pk_mul_f32 v[98:99], v[108:109], v[98:99] op_sel:[1,0]
	v_pk_fma_f32 v[54:55], v[52:53], v[96:97], v[98:99]
	v_add_f32_dpp v118, v118, v118 quad_perm:[1,0,3,2] row_mask:0xf bank_mask:0xf bound_ctrl:1
	v_add_f32_dpp v119, v119, v119 quad_perm:[1,0,3,2] row_mask:0xf bank_mask:0xf bound_ctrl:1
	s_nop 0
	ds_read_b128 v[112:115], v90 offset:0x4800
	v_add_f32_dpp v118, v118, v118 quad_perm:[2,3,0,1] row_mask:0xf bank_mask:0xf bound_ctrl:1
	s_nop 0
	ds_read_b128 v[96:99], v90 offset:0x800
	v_add_f32_dpp v118, v118, v118 row_half_mirror row_mask:0xf bank_mask:0xf bound_ctrl:1
	s_nop 0
	ds_write2_b32 v93, v1, v119 offset0:0 offset1:36
	v_add_f32_dpp v2, v118, v118 row_mirror row_mask:0xf bank_mask:0xf bound_ctrl:1
	v_add_f32_dpp v118, v118, v118 row_mirror row_mask:0xf bank_mask:0xf bound_ctrl:1
	s_nop 0
	s_waitcnt lgkmcnt(4)
	v_permlane16_swap_b32_e32 v118, v2
	v_add_f32_e32 v118, v118, v2
	v_pk_fma_f32 v[52:53], v[102:103], v[118:119], v[54:55] op_sel_hi:[1,0,1]
	v_pk_mul_f32 v[0:1], v[52:53], v[120:121] op_sel_hi:[0,1]
	v_pk_fma_f32 v[0:1], v[52:53], v[122:123], v[0:1] op_sel:[1,0,0]
	v_pk_mul_f32 v[126:127], v[110:111], v[126:127] op_sel_hi:[0,1]
	v_pk_fma_f32 v[54:55], v[52:53], v[124:125], v[126:127]
	v_add_f32_dpp v0, v0, v0 quad_perm:[1,0,3,2] row_mask:0xf bank_mask:0xf bound_ctrl:1
	v_add_f32_dpp v1, v1, v1 quad_perm:[1,0,3,2] row_mask:0xf bank_mask:0xf bound_ctrl:1
	s_nop 0
	ds_read_b128 v[120:123], v90 offset:0x4a00
	v_add_f32_dpp v0, v0, v0 quad_perm:[2,3,0,1] row_mask:0xf bank_mask:0xf bound_ctrl:1
	s_nop 0
	ds_read_b128 v[124:127], v90 offset:0xa00
	v_add_f32_dpp v0, v0, v0 row_half_mirror row_mask:0xf bank_mask:0xf bound_ctrl:1
	s_nop 0
	ds_read2st64_b32 v[108:109], v89 offset0:196 offset1:197
	ds_read2st64_b64 v[100:103], v88 offset0:68 offset1:69
	v_add_f32_dpp v2, v0, v0 row_mirror row_mask:0xf bank_mask:0xf bound_ctrl:1
	v_add_f32_dpp v0, v0, v0 row_mirror row_mask:0xf bank_mask:0xf bound_ctrl:1
	s_nop 0
	s_waitcnt lgkmcnt(7)
	v_permlane16_swap_b32_e32 v0, v2
	v_add_f32_e32 v0, v0, v2
	v_pk_fma_f32 v[52:53], v[104:105], v[0:1], v[54:55] op_sel_hi:[1,0,1]
	v_pk_mul_f32 v[118:119], v[52:53], v[4:5] op_sel_hi:[0,1]
	v_pk_fma_f32 v[118:119], v[52:53], v[6:7], v[118:119] op_sel:[1,0,0]
	v_pk_mul_f32 v[10:11], v[110:111], v[10:11] op_sel:[1,0]
	v_pk_fma_f32 v[54:55], v[52:53], v[8:9], v[10:11]
	v_add_f32_dpp v118, v118, v118 quad_perm:[1,0,3,2] row_mask:0xf bank_mask:0xf bound_ctrl:1
	v_add_f32_dpp v119, v119, v119 quad_perm:[1,0,3,2] row_mask:0xf bank_mask:0xf bound_ctrl:1
	s_nop 0
	ds_read_b128 v[4:7], v90 offset:0x4c00
	v_add_f32_dpp v118, v118, v118 quad_perm:[2,3,0,1] row_mask:0xf bank_mask:0xf bound_ctrl:1
	s_nop 0
	ds_read_b128 v[8:11], v90 offset:0xc00
	v_add_f32_dpp v118, v118, v118 row_half_mirror row_mask:0xf bank_mask:0xf bound_ctrl:1
	s_nop 0
	ds_write2_b32 v93, v1, v119 offset0:72 offset1:108
	v_add_f32_dpp v2, v118, v118 row_mirror row_mask:0xf bank_mask:0xf bound_ctrl:1
	v_add_f32_dpp v118, v118, v118 row_mirror row_mask:0xf bank_mask:0xf bound_ctrl:1
	s_nop 0
	s_waitcnt lgkmcnt(4)
	v_permlane16_swap_b32_e32 v118, v2
	v_add_f32_e32 v118, v118, v2
	v_pk_fma_f32 v[52:53], v[106:107], v[118:119], v[54:55] op_sel_hi:[1,0,1]
	v_pk_mul_f32 v[0:1], v[52:53], v[112:113] op_sel_hi:[0,1]
	v_pk_fma_f32 v[0:1], v[52:53], v[114:115], v[0:1] op_sel:[1,0,0]
	v_pk_mul_f32 v[98:99], v[108:109], v[98:99] op_sel_hi:[0,1]
	v_pk_fma_f32 v[54:55], v[52:53], v[96:97], v[98:99]
	v_add_f32_dpp v0, v0, v0 quad_perm:[1,0,3,2] row_mask:0xf bank_mask:0xf bound_ctrl:1
	v_add_f32_dpp v1, v1, v1 quad_perm:[1,0,3,2] row_mask:0xf bank_mask:0xf bound_ctrl:1
	s_nop 0
	ds_read_b128 v[112:115], v90 offset:0x4e00
	v_add_f32_dpp v0, v0, v0 quad_perm:[2,3,0,1] row_mask:0xf bank_mask:0xf bound_ctrl:1
	s_nop 0
	ds_read_b128 v[96:99], v90 offset:0xe00
	v_add_f32_dpp v0, v0, v0 row_half_mirror row_mask:0xf bank_mask:0xf bound_ctrl:1
	s_nop 0
	ds_read2st64_b32 v[110:111], v89 offset0:198 offset1:199
	ds_read2st64_b64 v[104:107], v88 offset0:70 offset1:71
	v_add_f32_dpp v2, v0, v0 row_mirror row_mask:0xf bank_mask:0xf bound_ctrl:1
	v_add_f32_dpp v0, v0, v0 row_mirror row_mask:0xf bank_mask:0xf bound_ctrl:1
	s_nop 0
	s_waitcnt lgkmcnt(7)
	v_permlane16_swap_b32_e32 v0, v2
	v_add_f32_e32 v0, v0, v2
	v_pk_fma_f32 v[52:53], v[100:101], v[0:1], v[54:55] op_sel_hi:[1,0,1]
	v_pk_mul_f32 v[118:119], v[52:53], v[120:121] op_sel_hi:[0,1]
	v_pk_fma_f32 v[118:119], v[52:53], v[122:123], v[118:119] op_sel:[1,0,0]
	v_pk_mul_f32 v[126:127], v[108:109], v[126:127] op_sel:[1,0]
	v_pk_fma_f32 v[54:55], v[52:53], v[124:125], v[126:127]
	v_add_f32_dpp v118, v118, v118 quad_perm:[1,0,3,2] row_mask:0xf bank_mask:0xf bound_ctrl:1
	v_add_f32_dpp v119, v119, v119 quad_perm:[1,0,3,2] row_mask:0xf bank_mask:0xf bound_ctrl:1
	s_nop 0
	ds_read_b128 v[120:123], v90 offset:0x5000
	v_add_f32_dpp v118, v118, v118 quad_perm:[2,3,0,1] row_mask:0xf bank_mask:0xf bound_ctrl:1
	s_nop 0
	ds_read_b128 v[124:127], v90 offset:0x1000
	v_add_f32_dpp v118, v118, v118 row_half_mirror row_mask:0xf bank_mask:0xf bound_ctrl:1
	s_nop 0
	ds_write2_b32 v93, v1, v119 offset0:144 offset1:180
	v_add_f32_dpp v2, v118, v118 row_mirror row_mask:0xf bank_mask:0xf bound_ctrl:1
	v_add_f32_dpp v118, v118, v118 row_mirror row_mask:0xf bank_mask:0xf bound_ctrl:1
	s_nop 0
	s_waitcnt lgkmcnt(4)
	v_permlane16_swap_b32_e32 v118, v2
	v_add_f32_e32 v118, v118, v2
	v_pk_fma_f32 v[52:53], v[102:103], v[118:119], v[54:55] op_sel_hi:[1,0,1]
	v_pk_mul_f32 v[0:1], v[52:53], v[4:5] op_sel_hi:[0,1]
	v_pk_fma_f32 v[0:1], v[52:53], v[6:7], v[0:1] op_sel:[1,0,0]
	v_pk_mul_f32 v[10:11], v[110:111], v[10:11] op_sel_hi:[0,1]
	v_pk_fma_f32 v[54:55], v[52:53], v[8:9], v[10:11]
	v_add_f32_dpp v0, v0, v0 quad_perm:[1,0,3,2] row_mask:0xf bank_mask:0xf bound_ctrl:1
	v_add_f32_dpp v1, v1, v1 quad_perm:[1,0,3,2] row_mask:0xf bank_mask:0xf bound_ctrl:1
	s_nop 0
	ds_read_b128 v[4:7], v90 offset:0x5200
	v_add_f32_dpp v0, v0, v0 quad_perm:[2,3,0,1] row_mask:0xf bank_mask:0xf bound_ctrl:1
	s_nop 0
	ds_read_b128 v[8:11], v90 offset:0x1200
	v_add_f32_dpp v0, v0, v0 row_half_mirror row_mask:0xf bank_mask:0xf bound_ctrl:1
	s_nop 0
	ds_read2st64_b32 v[108:109], v89 offset0:200 offset1:201
	ds_read2st64_b64 v[100:103], v88 offset0:72 offset1:73
	v_add_f32_dpp v2, v0, v0 row_mirror row_mask:0xf bank_mask:0xf bound_ctrl:1
	v_add_f32_dpp v0, v0, v0 row_mirror row_mask:0xf bank_mask:0xf bound_ctrl:1
	s_nop 0
	s_waitcnt lgkmcnt(7)
	v_permlane16_swap_b32_e32 v0, v2
	v_add_f32_e32 v0, v0, v2
	v_pk_fma_f32 v[52:53], v[104:105], v[0:1], v[54:55] op_sel_hi:[1,0,1]
	v_pk_mul_f32 v[118:119], v[52:53], v[112:113] op_sel_hi:[0,1]
	v_pk_fma_f32 v[118:119], v[52:53], v[114:115], v[118:119] op_sel:[1,0,0]
	v_pk_mul_f32 v[98:99], v[110:111], v[98:99] op_sel:[1,0]
	v_pk_fma_f32 v[54:55], v[52:53], v[96:97], v[98:99]
	v_add_f32_dpp v118, v118, v118 quad_perm:[1,0,3,2] row_mask:0xf bank_mask:0xf bound_ctrl:1
	v_add_f32_dpp v119, v119, v119 quad_perm:[1,0,3,2] row_mask:0xf bank_mask:0xf bound_ctrl:1
	s_nop 0
	ds_read_b128 v[112:115], v90 offset:0x5400
	v_add_f32_dpp v118, v118, v118 quad_perm:[2,3,0,1] row_mask:0xf bank_mask:0xf bound_ctrl:1
	s_nop 0
	ds_read_b128 v[96:99], v90 offset:0x1400
	v_add_f32_dpp v118, v118, v118 row_half_mirror row_mask:0xf bank_mask:0xf bound_ctrl:1
	s_nop 0
	ds_write2_b32 v93, v1, v119 offset0:216 offset1:252
	v_add_f32_dpp v2, v118, v118 row_mirror row_mask:0xf bank_mask:0xf bound_ctrl:1
	v_add_f32_dpp v118, v118, v118 row_mirror row_mask:0xf bank_mask:0xf bound_ctrl:1
	s_nop 0
	s_waitcnt lgkmcnt(4)
	v_permlane16_swap_b32_e32 v118, v2
	v_add_f32_e32 v118, v118, v2
	v_pk_fma_f32 v[52:53], v[106:107], v[118:119], v[54:55] op_sel_hi:[1,0,1]
	v_pk_mul_f32 v[0:1], v[52:53], v[120:121] op_sel_hi:[0,1]
	v_pk_fma_f32 v[0:1], v[52:53], v[122:123], v[0:1] op_sel:[1,0,0]
	v_pk_mul_f32 v[126:127], v[108:109], v[126:127] op_sel_hi:[0,1]
	v_pk_fma_f32 v[54:55], v[52:53], v[124:125], v[126:127]
	v_add_f32_dpp v0, v0, v0 quad_perm:[1,0,3,2] row_mask:0xf bank_mask:0xf bound_ctrl:1
	v_add_f32_dpp v1, v1, v1 quad_perm:[1,0,3,2] row_mask:0xf bank_mask:0xf bound_ctrl:1
	s_nop 0
	ds_read_b128 v[120:123], v90 offset:0x5600
	v_add_f32_dpp v0, v0, v0 quad_perm:[2,3,0,1] row_mask:0xf bank_mask:0xf bound_ctrl:1
	s_nop 0
	ds_read_b128 v[124:127], v90 offset:0x1600
	v_add_f32_dpp v0, v0, v0 row_half_mirror row_mask:0xf bank_mask:0xf bound_ctrl:1
	s_nop 0
	ds_read2st64_b32 v[110:111], v89 offset0:202 offset1:203
	ds_read2st64_b64 v[104:107], v88 offset0:74 offset1:75
	v_add_f32_dpp v2, v0, v0 row_mirror row_mask:0xf bank_mask:0xf bound_ctrl:1
	v_add_f32_dpp v0, v0, v0 row_mirror row_mask:0xf bank_mask:0xf bound_ctrl:1
	v_add_u32_e32 v93, 0x480, v93
	s_waitcnt lgkmcnt(7)
	v_permlane16_swap_b32_e32 v0, v2
	v_add_f32_e32 v0, v0, v2
	v_pk_fma_f32 v[52:53], v[100:101], v[0:1], v[54:55] op_sel_hi:[1,0,1]
	v_pk_mul_f32 v[118:119], v[52:53], v[4:5] op_sel_hi:[0,1]
	v_pk_fma_f32 v[118:119], v[52:53], v[6:7], v[118:119] op_sel:[1,0,0]
	v_pk_mul_f32 v[10:11], v[108:109], v[10:11] op_sel:[1,0]
	v_pk_fma_f32 v[54:55], v[52:53], v[8:9], v[10:11]
	v_add_f32_dpp v118, v118, v118 quad_perm:[1,0,3,2] row_mask:0xf bank_mask:0xf bound_ctrl:1
	v_add_f32_dpp v119, v119, v119 quad_perm:[1,0,3,2] row_mask:0xf bank_mask:0xf bound_ctrl:1
	s_nop 0
	ds_read_b128 v[4:7], v90 offset:0x5800
	v_add_f32_dpp v118, v118, v118 quad_perm:[2,3,0,1] row_mask:0xf bank_mask:0xf bound_ctrl:1
	s_nop 0
	ds_read_b128 v[8:11], v90 offset:0x1800
	v_add_f32_dpp v118, v118, v118 row_half_mirror row_mask:0xf bank_mask:0xf bound_ctrl:1
	s_nop 0
	ds_write2_b32 v93, v1, v119 offset0:0 offset1:36
	v_add_f32_dpp v2, v118, v118 row_mirror row_mask:0xf bank_mask:0xf bound_ctrl:1
	v_add_f32_dpp v118, v118, v118 row_mirror row_mask:0xf bank_mask:0xf bound_ctrl:1
	s_nop 0
	s_waitcnt lgkmcnt(4)
	v_permlane16_swap_b32_e32 v118, v2
	v_add_f32_e32 v118, v118, v2
	v_pk_fma_f32 v[52:53], v[102:103], v[118:119], v[54:55] op_sel_hi:[1,0,1]
	v_pk_mul_f32 v[0:1], v[52:53], v[112:113] op_sel_hi:[0,1]
	v_pk_fma_f32 v[0:1], v[52:53], v[114:115], v[0:1] op_sel:[1,0,0]
	v_pk_mul_f32 v[98:99], v[110:111], v[98:99] op_sel_hi:[0,1]
	v_pk_fma_f32 v[54:55], v[52:53], v[96:97], v[98:99]
	v_add_f32_dpp v0, v0, v0 quad_perm:[1,0,3,2] row_mask:0xf bank_mask:0xf bound_ctrl:1
	v_add_f32_dpp v1, v1, v1 quad_perm:[1,0,3,2] row_mask:0xf bank_mask:0xf bound_ctrl:1
	s_nop 0
	ds_read_b128 v[112:115], v90 offset:0x5a00
	v_add_f32_dpp v0, v0, v0 quad_perm:[2,3,0,1] row_mask:0xf bank_mask:0xf bound_ctrl:1
	s_nop 0
	ds_read_b128 v[96:99], v90 offset:0x1a00
	v_add_f32_dpp v0, v0, v0 row_half_mirror row_mask:0xf bank_mask:0xf bound_ctrl:1
	s_nop 0
	ds_read2st64_b32 v[108:109], v89 offset0:204 offset1:205
	ds_read2st64_b64 v[100:103], v88 offset0:76 offset1:77
	v_add_f32_dpp v2, v0, v0 row_mirror row_mask:0xf bank_mask:0xf bound_ctrl:1
	v_add_f32_dpp v0, v0, v0 row_mirror row_mask:0xf bank_mask:0xf bound_ctrl:1
	s_nop 0
	s_waitcnt lgkmcnt(7)
	v_permlane16_swap_b32_e32 v0, v2
	v_add_f32_e32 v0, v0, v2
	v_pk_fma_f32 v[52:53], v[104:105], v[0:1], v[54:55] op_sel_hi:[1,0,1]
	v_pk_mul_f32 v[118:119], v[52:53], v[120:121] op_sel_hi:[0,1]
	v_pk_fma_f32 v[118:119], v[52:53], v[122:123], v[118:119] op_sel:[1,0,0]
	v_pk_mul_f32 v[126:127], v[110:111], v[126:127] op_sel:[1,0]
	v_pk_fma_f32 v[54:55], v[52:53], v[124:125], v[126:127]
	v_add_f32_dpp v118, v118, v118 quad_perm:[1,0,3,2] row_mask:0xf bank_mask:0xf bound_ctrl:1
	v_add_f32_dpp v119, v119, v119 quad_perm:[1,0,3,2] row_mask:0xf bank_mask:0xf bound_ctrl:1
	s_nop 0
	ds_read_b128 v[120:123], v90 offset:0x5c00
	v_add_f32_dpp v118, v118, v118 quad_perm:[2,3,0,1] row_mask:0xf bank_mask:0xf bound_ctrl:1
	s_nop 0
	ds_read_b128 v[124:127], v90 offset:0x1c00
	v_add_f32_dpp v118, v118, v118 row_half_mirror row_mask:0xf bank_mask:0xf bound_ctrl:1
	s_nop 0
	ds_write2_b32 v93, v1, v119 offset0:72 offset1:108
	v_add_f32_dpp v2, v118, v118 row_mirror row_mask:0xf bank_mask:0xf bound_ctrl:1
	v_add_f32_dpp v118, v118, v118 row_mirror row_mask:0xf bank_mask:0xf bound_ctrl:1
	s_nop 0
	s_waitcnt lgkmcnt(4)
	v_permlane16_swap_b32_e32 v118, v2
	v_add_f32_e32 v118, v118, v2
	v_pk_fma_f32 v[52:53], v[106:107], v[118:119], v[54:55] op_sel_hi:[1,0,1]
	v_pk_mul_f32 v[0:1], v[52:53], v[4:5] op_sel_hi:[0,1]
	v_pk_fma_f32 v[0:1], v[52:53], v[6:7], v[0:1] op_sel:[1,0,0]
	v_pk_mul_f32 v[10:11], v[108:109], v[10:11] op_sel_hi:[0,1]
	v_pk_fma_f32 v[54:55], v[52:53], v[8:9], v[10:11]
	v_add_f32_dpp v0, v0, v0 quad_perm:[1,0,3,2] row_mask:0xf bank_mask:0xf bound_ctrl:1
	v_add_f32_dpp v1, v1, v1 quad_perm:[1,0,3,2] row_mask:0xf bank_mask:0xf bound_ctrl:1
	s_nop 0
	ds_read_b128 v[4:7], v90 offset:0x5e00
	v_add_f32_dpp v0, v0, v0 quad_perm:[2,3,0,1] row_mask:0xf bank_mask:0xf bound_ctrl:1
	s_nop 0
	ds_read_b128 v[8:11], v90 offset:0x1e00
	v_add_f32_dpp v0, v0, v0 row_half_mirror row_mask:0xf bank_mask:0xf bound_ctrl:1
	s_nop 0
	ds_read2st64_b32 v[110:111], v89 offset0:206 offset1:207
	ds_read2st64_b64 v[104:107], v88 offset0:78 offset1:79
	v_add_f32_dpp v2, v0, v0 row_mirror row_mask:0xf bank_mask:0xf bound_ctrl:1
	v_add_f32_dpp v0, v0, v0 row_mirror row_mask:0xf bank_mask:0xf bound_ctrl:1
	s_nop 0
	s_waitcnt lgkmcnt(7)
	v_permlane16_swap_b32_e32 v0, v2
	v_add_f32_e32 v0, v0, v2
	v_pk_fma_f32 v[52:53], v[100:101], v[0:1], v[54:55] op_sel_hi:[1,0,1]
	v_pk_mul_f32 v[118:119], v[52:53], v[112:113] op_sel_hi:[0,1]
	v_pk_fma_f32 v[118:119], v[52:53], v[114:115], v[118:119] op_sel:[1,0,0]
	v_pk_mul_f32 v[98:99], v[108:109], v[98:99] op_sel:[1,0]
	v_pk_fma_f32 v[54:55], v[52:53], v[96:97], v[98:99]
	v_add_f32_dpp v118, v118, v118 quad_perm:[1,0,3,2] row_mask:0xf bank_mask:0xf bound_ctrl:1
	v_add_f32_dpp v119, v119, v119 quad_perm:[1,0,3,2] row_mask:0xf bank_mask:0xf bound_ctrl:1
	s_nop 0
	ds_read_b128 v[112:115], v90 offset:0x6000
	v_add_f32_dpp v118, v118, v118 quad_perm:[2,3,0,1] row_mask:0xf bank_mask:0xf bound_ctrl:1
	s_nop 0
	ds_read_b128 v[96:99], v90 offset:0x2000
	v_add_f32_dpp v118, v118, v118 row_half_mirror row_mask:0xf bank_mask:0xf bound_ctrl:1
	s_nop 0
	ds_write2_b32 v93, v1, v119 offset0:144 offset1:180
	v_add_f32_dpp v2, v118, v118 row_mirror row_mask:0xf bank_mask:0xf bound_ctrl:1
	v_add_f32_dpp v118, v118, v118 row_mirror row_mask:0xf bank_mask:0xf bound_ctrl:1
	s_nop 0
	s_waitcnt lgkmcnt(4)
	v_permlane16_swap_b32_e32 v118, v2
	v_add_f32_e32 v118, v118, v2
	v_pk_fma_f32 v[52:53], v[102:103], v[118:119], v[54:55] op_sel_hi:[1,0,1]
	v_pk_mul_f32 v[0:1], v[52:53], v[120:121] op_sel_hi:[0,1]
	v_pk_fma_f32 v[0:1], v[52:53], v[122:123], v[0:1] op_sel:[1,0,0]
	v_pk_mul_f32 v[126:127], v[110:111], v[126:127] op_sel_hi:[0,1]
	v_pk_fma_f32 v[54:55], v[52:53], v[124:125], v[126:127]
	v_add_f32_dpp v0, v0, v0 quad_perm:[1,0,3,2] row_mask:0xf bank_mask:0xf bound_ctrl:1
	v_add_f32_dpp v1, v1, v1 quad_perm:[1,0,3,2] row_mask:0xf bank_mask:0xf bound_ctrl:1
	s_nop 0
	ds_read_b128 v[120:123], v90 offset:0x6200
	v_add_f32_dpp v0, v0, v0 quad_perm:[2,3,0,1] row_mask:0xf bank_mask:0xf bound_ctrl:1
	s_nop 0
	ds_read_b128 v[124:127], v90 offset:0x2200
	v_add_f32_dpp v0, v0, v0 row_half_mirror row_mask:0xf bank_mask:0xf bound_ctrl:1
	s_nop 0
	ds_read2st64_b32 v[108:109], v89 offset0:208 offset1:209
	ds_read2st64_b64 v[100:103], v88 offset0:80 offset1:81
	v_add_f32_dpp v2, v0, v0 row_mirror row_mask:0xf bank_mask:0xf bound_ctrl:1
	v_add_f32_dpp v0, v0, v0 row_mirror row_mask:0xf bank_mask:0xf bound_ctrl:1
	s_nop 0
	s_waitcnt lgkmcnt(7)
	v_permlane16_swap_b32_e32 v0, v2
	v_add_f32_e32 v0, v0, v2
	v_pk_fma_f32 v[52:53], v[104:105], v[0:1], v[54:55] op_sel_hi:[1,0,1]
	v_pk_mul_f32 v[118:119], v[52:53], v[4:5] op_sel_hi:[0,1]
	v_pk_fma_f32 v[118:119], v[52:53], v[6:7], v[118:119] op_sel:[1,0,0]
	v_pk_mul_f32 v[10:11], v[110:111], v[10:11] op_sel:[1,0]
	v_pk_fma_f32 v[54:55], v[52:53], v[8:9], v[10:11]
	v_add_f32_dpp v118, v118, v118 quad_perm:[1,0,3,2] row_mask:0xf bank_mask:0xf bound_ctrl:1
	v_add_f32_dpp v119, v119, v119 quad_perm:[1,0,3,2] row_mask:0xf bank_mask:0xf bound_ctrl:1
	s_nop 0
	ds_read_b128 v[4:7], v90 offset:0x6400
	v_add_f32_dpp v118, v118, v118 quad_perm:[2,3,0,1] row_mask:0xf bank_mask:0xf bound_ctrl:1
	s_nop 0
	ds_read_b128 v[8:11], v90 offset:0x2400
	v_add_f32_dpp v118, v118, v118 row_half_mirror row_mask:0xf bank_mask:0xf bound_ctrl:1
	s_nop 0
	ds_write2_b32 v93, v1, v119 offset0:216 offset1:252
	v_add_f32_dpp v2, v118, v118 row_mirror row_mask:0xf bank_mask:0xf bound_ctrl:1
	v_add_f32_dpp v118, v118, v118 row_mirror row_mask:0xf bank_mask:0xf bound_ctrl:1
	s_nop 0
	s_waitcnt lgkmcnt(4)
	v_permlane16_swap_b32_e32 v118, v2
	v_add_f32_e32 v118, v118, v2
	v_pk_fma_f32 v[52:53], v[106:107], v[118:119], v[54:55] op_sel_hi:[1,0,1]
	s_cmp_eq_u32 s88, 0x800000
	s_cbranch_scc1 .LBB0_684
	v_pk_mul_f32 v[0:1], v[52:53], v[112:113] op_sel_hi:[0,1]
	v_pk_fma_f32 v[0:1], v[52:53], v[114:115], v[0:1] op_sel:[1,0,0]
	v_pk_mul_f32 v[98:99], v[108:109], v[98:99] op_sel_hi:[0,1]
	v_pk_fma_f32 v[54:55], v[52:53], v[96:97], v[98:99]
	v_add_f32_dpp v0, v0, v0 quad_perm:[1,0,3,2] row_mask:0xf bank_mask:0xf bound_ctrl:1
	v_add_f32_dpp v1, v1, v1 quad_perm:[1,0,3,2] row_mask:0xf bank_mask:0xf bound_ctrl:1
	s_nop 0
	ds_read_b128 v[112:115], v90 offset:0x6600
	v_add_f32_dpp v0, v0, v0 quad_perm:[2,3,0,1] row_mask:0xf bank_mask:0xf bound_ctrl:1
	s_nop 0
	ds_read_b128 v[96:99], v90 offset:0x2600
	v_add_f32_dpp v0, v0, v0 row_half_mirror row_mask:0xf bank_mask:0xf bound_ctrl:1
	s_nop 0
	ds_read2st64_b32 v[110:111], v89 offset0:210 offset1:211
	ds_read2st64_b64 v[104:107], v88 offset0:82 offset1:83
	v_add_f32_dpp v2, v0, v0 row_mirror row_mask:0xf bank_mask:0xf bound_ctrl:1
	v_add_f32_dpp v0, v0, v0 row_mirror row_mask:0xf bank_mask:0xf bound_ctrl:1
	v_add_u32_e32 v93, 0x480, v93
	s_waitcnt lgkmcnt(7)
	v_permlane16_swap_b32_e32 v0, v2
	v_add_f32_e32 v0, v0, v2
	v_pk_fma_f32 v[52:53], v[100:101], v[0:1], v[54:55] op_sel_hi:[1,0,1]
	v_pk_mul_f32 v[118:119], v[52:53], v[120:121] op_sel_hi:[0,1]
	v_pk_fma_f32 v[118:119], v[52:53], v[122:123], v[118:119] op_sel:[1,0,0]
	v_pk_mul_f32 v[126:127], v[108:109], v[126:127] op_sel:[1,0]
	v_pk_fma_f32 v[54:55], v[52:53], v[124:125], v[126:127]
	v_add_f32_dpp v118, v118, v118 quad_perm:[1,0,3,2] row_mask:0xf bank_mask:0xf bound_ctrl:1
	v_add_f32_dpp v119, v119, v119 quad_perm:[1,0,3,2] row_mask:0xf bank_mask:0xf bound_ctrl:1
	s_nop 0
	ds_read_b128 v[120:123], v90 offset:0x6800
	v_add_f32_dpp v118, v118, v118 quad_perm:[2,3,0,1] row_mask:0xf bank_mask:0xf bound_ctrl:1
	s_nop 0
	ds_read_b128 v[124:127], v90 offset:0x2800
	v_add_f32_dpp v118, v118, v118 row_half_mirror row_mask:0xf bank_mask:0xf bound_ctrl:1
	s_nop 0
	ds_write2_b32 v93, v1, v119 offset0:0 offset1:36
	v_add_f32_dpp v2, v118, v118 row_mirror row_mask:0xf bank_mask:0xf bound_ctrl:1
	v_add_f32_dpp v118, v118, v118 row_mirror row_mask:0xf bank_mask:0xf bound_ctrl:1
	s_nop 0
	s_waitcnt lgkmcnt(4)
	v_permlane16_swap_b32_e32 v118, v2
	v_add_f32_e32 v118, v118, v2
	v_pk_fma_f32 v[52:53], v[102:103], v[118:119], v[54:55] op_sel_hi:[1,0,1]
	v_pk_mul_f32 v[0:1], v[52:53], v[4:5] op_sel_hi:[0,1]
	v_pk_fma_f32 v[0:1], v[52:53], v[6:7], v[0:1] op_sel:[1,0,0]
	v_pk_mul_f32 v[10:11], v[110:111], v[10:11] op_sel_hi:[0,1]
	v_pk_fma_f32 v[54:55], v[52:53], v[8:9], v[10:11]
	v_add_f32_dpp v0, v0, v0 quad_perm:[1,0,3,2] row_mask:0xf bank_mask:0xf bound_ctrl:1
	v_add_f32_dpp v1, v1, v1 quad_perm:[1,0,3,2] row_mask:0xf bank_mask:0xf bound_ctrl:1
	s_nop 0
	ds_read_b128 v[4:7], v90 offset:0x6a00
	v_add_f32_dpp v0, v0, v0 quad_perm:[2,3,0,1] row_mask:0xf bank_mask:0xf bound_ctrl:1
	s_nop 0
	ds_read_b128 v[8:11], v90 offset:0x2a00
	v_add_f32_dpp v0, v0, v0 row_half_mirror row_mask:0xf bank_mask:0xf bound_ctrl:1
	s_nop 0
	ds_read2st64_b32 v[108:109], v89 offset0:212 offset1:213
	ds_read2st64_b64 v[100:103], v88 offset0:84 offset1:85
	v_add_f32_dpp v2, v0, v0 row_mirror row_mask:0xf bank_mask:0xf bound_ctrl:1
	v_add_f32_dpp v0, v0, v0 row_mirror row_mask:0xf bank_mask:0xf bound_ctrl:1
	s_nop 0
	s_waitcnt lgkmcnt(7)
	v_permlane16_swap_b32_e32 v0, v2
	v_add_f32_e32 v0, v0, v2
	v_pk_fma_f32 v[52:53], v[104:105], v[0:1], v[54:55] op_sel_hi:[1,0,1]
	v_pk_mul_f32 v[118:119], v[52:53], v[112:113] op_sel_hi:[0,1]
	v_pk_fma_f32 v[118:119], v[52:53], v[114:115], v[118:119] op_sel:[1,0,0]
	v_pk_mul_f32 v[98:99], v[110:111], v[98:99] op_sel:[1,0]
	v_pk_fma_f32 v[54:55], v[52:53], v[96:97], v[98:99]
	v_add_f32_dpp v118, v118, v118 quad_perm:[1,0,3,2] row_mask:0xf bank_mask:0xf bound_ctrl:1
	v_add_f32_dpp v119, v119, v119 quad_perm:[1,0,3,2] row_mask:0xf bank_mask:0xf bound_ctrl:1
	s_nop 0
	ds_read_b128 v[112:115], v90 offset:0x6c00
	v_add_f32_dpp v118, v118, v118 quad_perm:[2,3,0,1] row_mask:0xf bank_mask:0xf bound_ctrl:1
	s_nop 0
	ds_read_b128 v[96:99], v90 offset:0x2c00
	v_add_f32_dpp v118, v118, v118 row_half_mirror row_mask:0xf bank_mask:0xf bound_ctrl:1
	s_nop 0
	ds_write2_b32 v93, v1, v119 offset0:72 offset1:108
	v_add_f32_dpp v2, v118, v118 row_mirror row_mask:0xf bank_mask:0xf bound_ctrl:1
	v_add_f32_dpp v118, v118, v118 row_mirror row_mask:0xf bank_mask:0xf bound_ctrl:1
	s_nop 0
	s_waitcnt lgkmcnt(4)
	v_permlane16_swap_b32_e32 v118, v2
	v_add_f32_e32 v118, v118, v2
	v_pk_fma_f32 v[52:53], v[106:107], v[118:119], v[54:55] op_sel_hi:[1,0,1]
	v_pk_mul_f32 v[0:1], v[52:53], v[120:121] op_sel_hi:[0,1]
	v_pk_fma_f32 v[0:1], v[52:53], v[122:123], v[0:1] op_sel:[1,0,0]
	v_pk_mul_f32 v[126:127], v[108:109], v[126:127] op_sel_hi:[0,1]
	v_pk_fma_f32 v[54:55], v[52:53], v[124:125], v[126:127]
	v_add_f32_dpp v0, v0, v0 quad_perm:[1,0,3,2] row_mask:0xf bank_mask:0xf bound_ctrl:1
	v_add_f32_dpp v1, v1, v1 quad_perm:[1,0,3,2] row_mask:0xf bank_mask:0xf bound_ctrl:1
	s_nop 0
	ds_read_b128 v[120:123], v90 offset:0x6e00
	v_add_f32_dpp v0, v0, v0 quad_perm:[2,3,0,1] row_mask:0xf bank_mask:0xf bound_ctrl:1
	s_nop 0
	ds_read_b128 v[124:127], v90 offset:0x2e00
	v_add_f32_dpp v0, v0, v0 row_half_mirror row_mask:0xf bank_mask:0xf bound_ctrl:1
	s_nop 0
	ds_read2st64_b32 v[110:111], v89 offset0:214 offset1:215
	ds_read2st64_b64 v[104:107], v88 offset0:86 offset1:87
	v_add_f32_dpp v2, v0, v0 row_mirror row_mask:0xf bank_mask:0xf bound_ctrl:1
	v_add_f32_dpp v0, v0, v0 row_mirror row_mask:0xf bank_mask:0xf bound_ctrl:1
	s_nop 0
	s_waitcnt lgkmcnt(7)
	v_permlane16_swap_b32_e32 v0, v2
	v_add_f32_e32 v0, v0, v2
	v_pk_fma_f32 v[52:53], v[100:101], v[0:1], v[54:55] op_sel_hi:[1,0,1]
	v_pk_mul_f32 v[118:119], v[52:53], v[4:5] op_sel_hi:[0,1]
	v_pk_fma_f32 v[118:119], v[52:53], v[6:7], v[118:119] op_sel:[1,0,0]
	v_pk_mul_f32 v[10:11], v[108:109], v[10:11] op_sel:[1,0]
	v_pk_fma_f32 v[54:55], v[52:53], v[8:9], v[10:11]
	v_add_f32_dpp v118, v118, v118 quad_perm:[1,0,3,2] row_mask:0xf bank_mask:0xf bound_ctrl:1
	v_add_f32_dpp v119, v119, v119 quad_perm:[1,0,3,2] row_mask:0xf bank_mask:0xf bound_ctrl:1
	s_nop 0
	ds_read_b128 v[4:7], v90 offset:0x7000
	v_add_f32_dpp v118, v118, v118 quad_perm:[2,3,0,1] row_mask:0xf bank_mask:0xf bound_ctrl:1
	s_nop 0
	ds_read_b128 v[8:11], v90 offset:0x3000
	v_add_f32_dpp v118, v118, v118 row_half_mirror row_mask:0xf bank_mask:0xf bound_ctrl:1
	s_nop 0
	ds_write2_b32 v93, v1, v119 offset0:144 offset1:180
	v_add_f32_dpp v2, v118, v118 row_mirror row_mask:0xf bank_mask:0xf bound_ctrl:1
	v_add_f32_dpp v118, v118, v118 row_mirror row_mask:0xf bank_mask:0xf bound_ctrl:1
	s_nop 0
	s_waitcnt lgkmcnt(4)
	v_permlane16_swap_b32_e32 v118, v2
	v_add_f32_e32 v118, v118, v2
	v_pk_fma_f32 v[52:53], v[102:103], v[118:119], v[54:55] op_sel_hi:[1,0,1]
	v_pk_mul_f32 v[0:1], v[52:53], v[112:113] op_sel_hi:[0,1]
	v_pk_fma_f32 v[0:1], v[52:53], v[114:115], v[0:1] op_sel:[1,0,0]
	v_pk_mul_f32 v[98:99], v[110:111], v[98:99] op_sel_hi:[0,1]
	v_pk_fma_f32 v[54:55], v[52:53], v[96:97], v[98:99]
	v_add_f32_dpp v0, v0, v0 quad_perm:[1,0,3,2] row_mask:0xf bank_mask:0xf bound_ctrl:1
	v_add_f32_dpp v1, v1, v1 quad_perm:[1,0,3,2] row_mask:0xf bank_mask:0xf bound_ctrl:1
	s_nop 0
	ds_read_b128 v[112:115], v90 offset:0x7200
	v_add_f32_dpp v0, v0, v0 quad_perm:[2,3,0,1] row_mask:0xf bank_mask:0xf bound_ctrl:1
	s_nop 0
	ds_read_b128 v[96:99], v90 offset:0x3200
	v_add_f32_dpp v0, v0, v0 row_half_mirror row_mask:0xf bank_mask:0xf bound_ctrl:1
	s_nop 0
	ds_read2st64_b32 v[108:109], v89 offset0:216 offset1:217
	ds_read2st64_b64 v[100:103], v88 offset0:88 offset1:89
	v_add_f32_dpp v2, v0, v0 row_mirror row_mask:0xf bank_mask:0xf bound_ctrl:1
	v_add_f32_dpp v0, v0, v0 row_mirror row_mask:0xf bank_mask:0xf bound_ctrl:1
	s_nop 0
	s_waitcnt lgkmcnt(7)
	v_permlane16_swap_b32_e32 v0, v2
	v_add_f32_e32 v0, v0, v2
	v_pk_fma_f32 v[52:53], v[104:105], v[0:1], v[54:55] op_sel_hi:[1,0,1]
	v_pk_mul_f32 v[118:119], v[52:53], v[120:121] op_sel_hi:[0,1]
	v_pk_fma_f32 v[118:119], v[52:53], v[122:123], v[118:119] op_sel:[1,0,0]
	v_pk_mul_f32 v[126:127], v[110:111], v[126:127] op_sel:[1,0]
	v_pk_fma_f32 v[54:55], v[52:53], v[124:125], v[126:127]
	v_add_f32_dpp v118, v118, v118 quad_perm:[1,0,3,2] row_mask:0xf bank_mask:0xf bound_ctrl:1
	v_add_f32_dpp v119, v119, v119 quad_perm:[1,0,3,2] row_mask:0xf bank_mask:0xf bound_ctrl:1
	s_nop 0
	ds_read_b128 v[120:123], v90 offset:0x7400
	v_add_f32_dpp v118, v118, v118 quad_perm:[2,3,0,1] row_mask:0xf bank_mask:0xf bound_ctrl:1
	s_nop 0
	ds_read_b128 v[124:127], v90 offset:0x3400
	v_add_f32_dpp v118, v118, v118 row_half_mirror row_mask:0xf bank_mask:0xf bound_ctrl:1
	s_nop 0
	ds_write2_b32 v93, v1, v119 offset0:216 offset1:252
	v_add_f32_dpp v2, v118, v118 row_mirror row_mask:0xf bank_mask:0xf bound_ctrl:1
	v_add_f32_dpp v118, v118, v118 row_mirror row_mask:0xf bank_mask:0xf bound_ctrl:1
	s_nop 0
	s_waitcnt lgkmcnt(4)
	v_permlane16_swap_b32_e32 v118, v2
	v_add_f32_e32 v118, v118, v2
	v_pk_fma_f32 v[52:53], v[106:107], v[118:119], v[54:55] op_sel_hi:[1,0,1]
	v_pk_mul_f32 v[0:1], v[52:53], v[4:5] op_sel_hi:[0,1]
	v_pk_fma_f32 v[0:1], v[52:53], v[6:7], v[0:1] op_sel:[1,0,0]
	v_pk_mul_f32 v[10:11], v[108:109], v[10:11] op_sel_hi:[0,1]
	v_pk_fma_f32 v[54:55], v[52:53], v[8:9], v[10:11]
	v_add_f32_dpp v0, v0, v0 quad_perm:[1,0,3,2] row_mask:0xf bank_mask:0xf bound_ctrl:1
	v_add_f32_dpp v1, v1, v1 quad_perm:[1,0,3,2] row_mask:0xf bank_mask:0xf bound_ctrl:1
	s_nop 0
	ds_read_b128 v[4:7], v90 offset:0x7600
	v_add_f32_dpp v0, v0, v0 quad_perm:[2,3,0,1] row_mask:0xf bank_mask:0xf bound_ctrl:1
	s_nop 0
	ds_read_b128 v[8:11], v90 offset:0x3600
	v_add_f32_dpp v0, v0, v0 row_half_mirror row_mask:0xf bank_mask:0xf bound_ctrl:1
	s_nop 0
	ds_read2st64_b32 v[110:111], v89 offset0:218 offset1:219
	ds_read2st64_b64 v[104:107], v88 offset0:90 offset1:91
	v_add_f32_dpp v2, v0, v0 row_mirror row_mask:0xf bank_mask:0xf bound_ctrl:1
	v_add_f32_dpp v0, v0, v0 row_mirror row_mask:0xf bank_mask:0xf bound_ctrl:1
	v_add_u32_e32 v93, 0x480, v93
	s_waitcnt lgkmcnt(7)
	v_permlane16_swap_b32_e32 v0, v2
	v_add_f32_e32 v0, v0, v2
	v_pk_fma_f32 v[52:53], v[100:101], v[0:1], v[54:55] op_sel_hi:[1,0,1]
	v_pk_mul_f32 v[118:119], v[52:53], v[112:113] op_sel_hi:[0,1]
	v_pk_fma_f32 v[118:119], v[52:53], v[114:115], v[118:119] op_sel:[1,0,0]
	v_pk_mul_f32 v[98:99], v[108:109], v[98:99] op_sel:[1,0]
	v_pk_fma_f32 v[54:55], v[52:53], v[96:97], v[98:99]
	v_add_f32_dpp v118, v118, v118 quad_perm:[1,0,3,2] row_mask:0xf bank_mask:0xf bound_ctrl:1
	v_add_f32_dpp v119, v119, v119 quad_perm:[1,0,3,2] row_mask:0xf bank_mask:0xf bound_ctrl:1
	s_nop 0
	ds_read_b128 v[112:115], v90 offset:0x7800
	v_add_f32_dpp v118, v118, v118 quad_perm:[2,3,0,1] row_mask:0xf bank_mask:0xf bound_ctrl:1
	s_nop 0
	ds_read_b128 v[96:99], v90 offset:0x3800
	v_add_f32_dpp v118, v118, v118 row_half_mirror row_mask:0xf bank_mask:0xf bound_ctrl:1
	s_nop 0
	ds_write2_b32 v93, v1, v119 offset0:0 offset1:36
	v_add_f32_dpp v2, v118, v118 row_mirror row_mask:0xf bank_mask:0xf bound_ctrl:1
	v_add_f32_dpp v118, v118, v118 row_mirror row_mask:0xf bank_mask:0xf bound_ctrl:1
	s_nop 0
	s_waitcnt lgkmcnt(4)
	v_permlane16_swap_b32_e32 v118, v2
	v_add_f32_e32 v118, v118, v2
	v_pk_fma_f32 v[52:53], v[102:103], v[118:119], v[54:55] op_sel_hi:[1,0,1]
	v_pk_mul_f32 v[0:1], v[52:53], v[120:121] op_sel_hi:[0,1]
	v_pk_fma_f32 v[0:1], v[52:53], v[122:123], v[0:1] op_sel:[1,0,0]
	v_pk_mul_f32 v[126:127], v[110:111], v[126:127] op_sel_hi:[0,1]
	v_pk_fma_f32 v[54:55], v[52:53], v[124:125], v[126:127]
	v_add_f32_dpp v0, v0, v0 quad_perm:[1,0,3,2] row_mask:0xf bank_mask:0xf bound_ctrl:1
	v_add_f32_dpp v1, v1, v1 quad_perm:[1,0,3,2] row_mask:0xf bank_mask:0xf bound_ctrl:1
	s_nop 0
	ds_read_b128 v[120:123], v90 offset:0x7a00
	v_add_f32_dpp v0, v0, v0 quad_perm:[2,3,0,1] row_mask:0xf bank_mask:0xf bound_ctrl:1
	s_nop 0
	ds_read_b128 v[124:127], v90 offset:0x3a00
	v_add_f32_dpp v0, v0, v0 row_half_mirror row_mask:0xf bank_mask:0xf bound_ctrl:1
	s_nop 0
	ds_read2st64_b32 v[108:109], v89 offset0:220 offset1:221
	ds_read2st64_b64 v[100:103], v88 offset0:92 offset1:93
	v_add_f32_dpp v2, v0, v0 row_mirror row_mask:0xf bank_mask:0xf bound_ctrl:1
	v_add_f32_dpp v0, v0, v0 row_mirror row_mask:0xf bank_mask:0xf bound_ctrl:1
	s_nop 0
	s_waitcnt lgkmcnt(7)
	v_permlane16_swap_b32_e32 v0, v2
	v_add_f32_e32 v0, v0, v2
	v_pk_fma_f32 v[52:53], v[104:105], v[0:1], v[54:55] op_sel_hi:[1,0,1]
	v_pk_mul_f32 v[118:119], v[52:53], v[4:5] op_sel_hi:[0,1]
	v_pk_fma_f32 v[118:119], v[52:53], v[6:7], v[118:119] op_sel:[1,0,0]
	v_pk_mul_f32 v[10:11], v[110:111], v[10:11] op_sel:[1,0]
	v_pk_fma_f32 v[54:55], v[52:53], v[8:9], v[10:11]
	v_add_f32_dpp v118, v118, v118 quad_perm:[1,0,3,2] row_mask:0xf bank_mask:0xf bound_ctrl:1
	v_add_f32_dpp v119, v119, v119 quad_perm:[1,0,3,2] row_mask:0xf bank_mask:0xf bound_ctrl:1
	s_nop 0
	ds_read_b128 v[4:7], v90 offset:0x7c00
	v_add_f32_dpp v118, v118, v118 quad_perm:[2,3,0,1] row_mask:0xf bank_mask:0xf bound_ctrl:1
	s_nop 0
	ds_read_b128 v[8:11], v90 offset:0x3c00
	v_add_f32_dpp v118, v118, v118 row_half_mirror row_mask:0xf bank_mask:0xf bound_ctrl:1
	s_nop 0
	ds_write2_b32 v93, v1, v119 offset0:72 offset1:108
	v_add_f32_dpp v2, v118, v118 row_mirror row_mask:0xf bank_mask:0xf bound_ctrl:1
	v_add_f32_dpp v118, v118, v118 row_mirror row_mask:0xf bank_mask:0xf bound_ctrl:1
	s_nop 0
	s_waitcnt lgkmcnt(4)
	v_permlane16_swap_b32_e32 v118, v2
	v_add_f32_e32 v118, v118, v2
	v_pk_fma_f32 v[52:53], v[106:107], v[118:119], v[54:55] op_sel_hi:[1,0,1]
	v_pk_mul_f32 v[0:1], v[52:53], v[112:113] op_sel_hi:[0,1]
	v_pk_fma_f32 v[0:1], v[52:53], v[114:115], v[0:1] op_sel:[1,0,0]
	v_pk_mul_f32 v[98:99], v[108:109], v[98:99] op_sel_hi:[0,1]
	v_pk_fma_f32 v[54:55], v[52:53], v[96:97], v[98:99]
	v_add_f32_dpp v0, v0, v0 quad_perm:[1,0,3,2] row_mask:0xf bank_mask:0xf bound_ctrl:1
	v_add_f32_dpp v1, v1, v1 quad_perm:[1,0,3,2] row_mask:0xf bank_mask:0xf bound_ctrl:1
	s_nop 0
	ds_read_b128 v[112:115], v90 offset:0x7e00
	v_add_f32_dpp v0, v0, v0 quad_perm:[2,3,0,1] row_mask:0xf bank_mask:0xf bound_ctrl:1
	s_nop 0
	ds_read_b128 v[96:99], v90 offset:0x3e00
	v_add_f32_dpp v0, v0, v0 row_half_mirror row_mask:0xf bank_mask:0xf bound_ctrl:1
	s_nop 0
	ds_read2st64_b32 v[110:111], v89 offset0:222 offset1:223
	ds_read2st64_b64 v[104:107], v88 offset0:94 offset1:95
	v_add_f32_dpp v2, v0, v0 row_mirror row_mask:0xf bank_mask:0xf bound_ctrl:1
	v_add_f32_dpp v0, v0, v0 row_mirror row_mask:0xf bank_mask:0xf bound_ctrl:1
	s_nop 0
	s_waitcnt lgkmcnt(7)
	v_permlane16_swap_b32_e32 v0, v2
	v_add_f32_e32 v0, v0, v2
	v_pk_fma_f32 v[52:53], v[100:101], v[0:1], v[54:55] op_sel_hi:[1,0,1]
	v_pk_mul_f32 v[118:119], v[52:53], v[120:121] op_sel_hi:[0,1]
	v_pk_fma_f32 v[118:119], v[52:53], v[122:123], v[118:119] op_sel:[1,0,0]
	v_pk_mul_f32 v[126:127], v[108:109], v[126:127] op_sel:[1,0]
	v_pk_fma_f32 v[54:55], v[52:53], v[124:125], v[126:127]
	v_add_f32_dpp v118, v118, v118 quad_perm:[1,0,3,2] row_mask:0xf bank_mask:0xf bound_ctrl:1
	v_add_f32_dpp v119, v119, v119 quad_perm:[1,0,3,2] row_mask:0xf bank_mask:0xf bound_ctrl:1
	s_nop 0
	s_nop 0
	v_add_f32_dpp v118, v118, v118 quad_perm:[2,3,0,1] row_mask:0xf bank_mask:0xf bound_ctrl:1
	s_nop 0
	s_nop 0
	v_add_f32_dpp v118, v118, v118 row_half_mirror row_mask:0xf bank_mask:0xf bound_ctrl:1
	s_nop 0
	ds_write2_b32 v93, v1, v119 offset0:144 offset1:180
	v_add_f32_dpp v2, v118, v118 row_mirror row_mask:0xf bank_mask:0xf bound_ctrl:1
	v_add_f32_dpp v118, v118, v118 row_mirror row_mask:0xf bank_mask:0xf bound_ctrl:1
	s_nop 0
	s_waitcnt lgkmcnt(2)
	v_permlane16_swap_b32_e32 v118, v2
	v_add_f32_e32 v118, v118, v2
	v_pk_fma_f32 v[52:53], v[102:103], v[118:119], v[54:55] op_sel_hi:[1,0,1]
	v_pk_mul_f32 v[0:1], v[52:53], v[4:5] op_sel_hi:[0,1]
	v_pk_fma_f32 v[0:1], v[52:53], v[6:7], v[0:1] op_sel:[1,0,0]
	v_pk_mul_f32 v[10:11], v[110:111], v[10:11] op_sel_hi:[0,1]
	v_pk_fma_f32 v[54:55], v[52:53], v[8:9], v[10:11]
	v_add_f32_dpp v0, v0, v0 quad_perm:[1,0,3,2] row_mask:0xf bank_mask:0xf bound_ctrl:1
	v_add_f32_dpp v1, v1, v1 quad_perm:[1,0,3,2] row_mask:0xf bank_mask:0xf bound_ctrl:1
	s_nop 0
	s_nop 0
	v_add_f32_dpp v0, v0, v0 quad_perm:[2,3,0,1] row_mask:0xf bank_mask:0xf bound_ctrl:1
	s_nop 0
	s_nop 0
	v_add_f32_dpp v0, v0, v0 row_half_mirror row_mask:0xf bank_mask:0xf bound_ctrl:1
	s_nop 0
	s_nop 0
	v_add_f32_dpp v2, v0, v0 row_mirror row_mask:0xf bank_mask:0xf bound_ctrl:1
	v_add_f32_dpp v0, v0, v0 row_mirror row_mask:0xf bank_mask:0xf bound_ctrl:1
	s_nop 0
	s_waitcnt lgkmcnt(1)
	v_permlane16_swap_b32_e32 v0, v2
	v_add_f32_e32 v0, v0, v2
	v_pk_fma_f32 v[52:53], v[104:105], v[0:1], v[54:55] op_sel_hi:[1,0,1]
	v_pk_mul_f32 v[118:119], v[52:53], v[112:113] op_sel_hi:[0,1]
	v_pk_fma_f32 v[118:119], v[52:53], v[114:115], v[118:119] op_sel:[1,0,0]
	v_pk_mul_f32 v[98:99], v[110:111], v[98:99] op_sel:[1,0]
	v_pk_fma_f32 v[54:55], v[52:53], v[96:97], v[98:99]
	v_add_f32_dpp v118, v118, v118 quad_perm:[1,0,3,2] row_mask:0xf bank_mask:0xf bound_ctrl:1
	v_add_f32_dpp v119, v119, v119 quad_perm:[1,0,3,2] row_mask:0xf bank_mask:0xf bound_ctrl:1
	s_nop 0
	s_nop 0
	v_add_f32_dpp v118, v118, v118 quad_perm:[2,3,0,1] row_mask:0xf bank_mask:0xf bound_ctrl:1
	s_nop 0
	s_nop 0
	v_add_f32_dpp v118, v118, v118 row_half_mirror row_mask:0xf bank_mask:0xf bound_ctrl:1
	s_nop 0
	ds_write2_b32 v93, v1, v119 offset0:216 offset1:252
	v_add_f32_dpp v2, v118, v118 row_mirror row_mask:0xf bank_mask:0xf bound_ctrl:1
	v_add_f32_dpp v118, v118, v118 row_mirror row_mask:0xf bank_mask:0xf bound_ctrl:1
	s_nop 0
	s_nop 0
	v_permlane16_swap_b32_e32 v118, v2
	v_add_f32_e32 v118, v118, v2
	v_pk_fma_f32 v[52:53], v[106:107], v[118:119], v[54:55] op_sel_hi:[1,0,1]
	ds_read_b128 v[104:107], v92
	ds_read_b128 v[116:119], v92 offset:16
	ds_read_b128 v[120:123], v92 offset:32
	ds_read_b128 v[124:127], v92 offset:48
	s_min_u32 s83, s31, 32
	v_cmp_gt_u32_e32 vcc, s83, v87
	s_cmp_lg_u32 s88, 0
	s_cselect_b64 s[8:9], -1, 0
	v_cmp_ne_u32_e64 s[6:7], 0, v87
	s_or_b64 s[6:7], s[6:7], s[8:9]
	s_and_b64 s[8:9], vcc, s[6:7]
	v_lshl_add_u64 v[0:1], v[50:51], 0, s[88:89]
	v_lshl_add_u64 v[0:1], v[94:95], 0, v[0:1]
	v_add_co_u32_e32 v0, vcc, 0x10698000, v0
	s_nop 1
	v_addc_co_u32_e32 v1, vcc, 0, v1, vcc
	s_barrier
	s_add_i32 s30, s30, 1
	s_add_u32 s88, s88, 0x10000
	s_addc_u32 s89, s89, 0
	s_sub_i32 s31, s31, 32
	s_bitcmp1_b32 s30, 0
	s_cselect_b32 s6, 0xe000, 0
	v_add_u32_e32 v90, s6, v58
	v_sub_u32_e32 v88, v90, v61
	v_add_u32_e32 v89, s6, v86
	s_nop 0
	ds_read_b128 v[4:7], v90 offset:0x4000
	ds_read_b128 v[8:11], v90 offset:0x0
	ds_read2st64_b32 v[108:109], v89 offset0:192 offset1:193
	ds_read2st64_b64 v[100:103], v88 offset0:64 offset1:65
	ds_read_b128 v[112:115], v90 offset:0x4200
	ds_read_b128 v[96:99], v90 offset:0x200
	v_mov_b32_e32 v93, v91
	s_waitcnt lgkmcnt(6)
	v_add_f32_e32 v104, v104, v105
	v_add_f32_e32 v106, v106, v107
	v_add_f32_e32 v116, v116, v117
	v_add_f32_e32 v118, v118, v119
	v_add_f32_e32 v120, v120, v121
	v_add_f32_e32 v122, v122, v123
	v_add_f32_e32 v124, v124, v125
	v_add_f32_e32 v126, v126, v127
	v_add_f32_e32 v104, v104, v106
	v_add_f32_e32 v116, v116, v118
	v_add_f32_e32 v120, v120, v122
	v_add_f32_e32 v124, v124, v126
	v_add_f32_e32 v104, v104, v116
	v_add_f32_e32 v120, v120, v124
	v_add_f32_e32 v104, v104, v120
	s_and_saveexec_b64 s[6:7], s[8:9]
	global_store_dword v[0:1], v104, off
	s_or_b64 exec, exec, s[6:7]
	ds_read_b128 v[120:123], v90 offset:0x4400
	ds_read_b128 v[124:127], v90 offset:0x400
	s_waitcnt lgkmcnt(5)
	s_branch .Lrw_steps
